# MIX phase order swap on odd workgroups (mix within each XCD) instead of by XCD half
# speedup vs baseline: 1.0049x; 1.0019x over previous
; #define GEMMCALL if (0)
; #define FRESH_TID() asm volatile("" : "+v"(tid))
; __global__ void __launch_bounds__(NTHREADS, 2) mega(Params p) {
;     ...
;         {
;             for (int rep = 0; rep < REP_FOUR; ++rep) { FRESH_TID(); fft_phase(p, lds, tid); }
;             if (l == 0) {
;                 pg8::Gemm g{(const bf16_t*)(ws + WS_CTC), (const bf16_t*)(ws + WS_ZTC), 256, 2048, 512}; pg8::StaticOrder S; S.init(256, 2048, G, (int)blockIdx.x);
;                 EpiStore<0> E{MIX + (size_t)MX * KOUT + 512, KOUT, (size_t)256 * KOUT};
;                 GEMMCALL pg8::gemm_phase<EpiStore<0>, pg8::StaticOrder, true, true>(lds, g, S, E);
;             }
;             __syncthreads();
;             for (int rep = 0; rep < REP_ATTN; ++rep) { FRESH_TID(); attn_phase(p, l, lds, tid); }
;         }
.LBB0_452:
	s_or_b64 exec, exec, s[0:1]
	v_readlane_b32 s0, v254, 56
	v_readlane_b32 s1, v254, 57
	s_andn2_b64 vcc, exec, s[0:1]
	s_waitcnt lgkmcnt(0)
	s_barrier
	s_mov_b32 s68, 0
	s_bitcmp1_b32 s2, 0
	s_cbranch_scc0 .Lmix_norm
	s_mov_b32 s68, 1
	s_branch .LBB0_455
